# v16 + mLSTM chunk loop: next-chunk address calc hoisted to loop top, sa[row] LDS reads issued early with counted lgkmcnt
# speedup vs baseline: 1.0057x; 1.0041x over previous
; #define LAS __attribute__((address_space(3)))
; DI unsigned pk2(float lo, float hi) { f32x2 v = {lo, hi}; bf16x2_t b = __builtin_convertvector(v, bf16x2_t); return __builtin_bit_cast(unsigned, b); }
; DI float bflo(unsigned u) { return __uint_as_float(u << 16); }
; DI float bfhi(unsigned u) { return __uint_as_float(u & 0xffff0000u); }
; #define GLOAD(c) do { const float* g0 = gates + MTOK((c) * 128 + 2 * lane) * 16; const float* g1 = gates + MTOK((c) * 128 + 2 * lane + 1) * 16; \
;                 gi0 = g0[gcol]; gf0 = g0[gcol + 4]; gi1 = g1[gcol]; gf1 = g1[gcol + 4]; } while (0)
; DI void mlstm_phase(LAS unsigned char* lds, const bf16_t* proj, const float* gates, bf16_t* Hfw, bf16_t* Hbw, int G, int bid) {
;     ...
;         for (int c = 0; c < nc; ++c) {
;             const int cur = c & 1;
;             LAS float* sa = smal + cur * 388; LAS float* sM = sa + 128; LAS float* sb = sa + 256; LAS float* scl = sa + 384;
;             const float mp = scl[0], M127 = scl[1];
; #pragma unroll
;             for (int i = 0; i < 4; ++i) { const int ci = tid + 512 * i, row = ci >> 4, ch = ci & 15;
;                 *(LAS u32x4*)(Qs + row * MQ_STRIDE + ch * 16) = pq[i]; *(LAS u32x4*)(Ks + row * MQ_STRIDE + ch * 16) = pk[i]; }
; #pragma unroll
;             for (int i = 0; i < 2; ++i) { const int ci = tid + 512 * i, row = ci >> 3, ch = ci & 7;
;                 *(LAS u32x4*)(Vs + row * MV_STRIDE + ch * 16) = pv[i];
;                 const float wsv = __expf(sa[row] - M127);
;                 u32x4 w;
; #pragma unroll
;                 for (int e = 0; e < 4; ++e) w[e] = pk2(bflo(pv[i][e]) * wsv, bfhi(pv[i][e]) * wsv);
;                 *(LAS u32x4*)(VWs + row * MV_STRIDE + ch * 16) = w;
;                 if (ch == 0) { const u32x4 x0 = {pk2(wsv, 0.f), 0u, 0u, 0u}, x1 = {0u, 0u, 0u, 0u};
;                     *(LAS u32x4*)(VWs + row * MV_STRIDE + 128) = x0; *(LAS u32x4*)(VWs + row * MV_STRIDE + 144) = x1; }
;             }
;             if (c + 1 < nc) { MLOAD(c + 1); if (wid == 2) GLOAD(c + 1); }
.LBB0_836:
	v_add_u32_e32 v0, 0x80, v155
	v_sub_u32_e32 v2, 0xffffff7f, v155
	v_add_u32_e32 v0, s48, v0
	v_add_u32_e32 v2, s46, v2
	v_cndmask_b32_e64 v2, v2, v0, s[90:91]
	v_ashrrev_i32_e32 v3, 31, v2
	v_lshl_add_u64 v[2:3], v[2:3], 0, s[96:97]
	v_mad_u64_u32 v[212:213], s[92:93], v2, s33, v[138:139]
	v_add_u32_e32 v0, 0x80, v156
	v_sub_u32_e32 v2, 0xffffff7f, v156
	v_add_u32_e32 v0, s48, v0
	v_add_u32_e32 v2, s46, v2
	v_cndmask_b32_e64 v2, v2, v0, s[90:91]
	v_mad_i32_i24 v213, v3, s33, v213
	v_ashrrev_i32_e32 v3, 31, v2
	v_lshl_add_u64 v[2:3], v[2:3], 0, s[96:97]
	v_mad_u64_u32 v[214:215], s[92:93], v2, s33, v[138:139]
	v_add_u32_e32 v0, 0x80, v157
	v_sub_u32_e32 v2, 0xffffff7f, v157
	v_add_u32_e32 v0, s48, v0
	v_add_u32_e32 v2, s46, v2
	v_cndmask_b32_e64 v2, v2, v0, s[90:91]
	v_mad_i32_i24 v215, v3, s33, v215
	v_ashrrev_i32_e32 v3, 31, v2
	v_lshl_add_u64 v[2:3], v[2:3], 0, s[96:97]
	v_mad_u64_u32 v[216:217], s[92:93], v2, s33, v[138:139]
	v_add_u32_e32 v0, 0x80, v158
	v_sub_u32_e32 v2, 0xffffff7f, v158
	v_add_u32_e32 v0, s48, v0
	v_add_u32_e32 v2, s46, v2
	v_cndmask_b32_e64 v2, v2, v0, s[90:91]
	v_mad_i32_i24 v217, v3, s33, v217
	v_ashrrev_i32_e32 v3, 31, v2
	v_lshl_add_u64 v[2:3], v[2:3], 0, s[96:97]
	v_mad_u64_u32 v[218:219], s[92:93], v2, s33, v[138:139]
	v_add_u32_e32 v0, 0x80, v159
	v_sub_u32_e32 v2, 0xffffff7f, v159
	v_add_u32_e32 v0, s48, v0
	v_add_u32_e32 v2, s46, v2
	v_cndmask_b32_e64 v2, v2, v0, s[90:91]
	v_mad_i32_i24 v219, v3, s33, v219
	v_ashrrev_i32_e32 v3, 31, v2
	v_lshl_add_u64 v[2:3], v[2:3], 0, s[96:97]
	v_mad_u64_u32 v[220:221], s[92:93], v2, s33, v[140:141]
	v_add_u32_e32 v0, 0x80, v160
	v_sub_u32_e32 v2, 0xffffff7f, v160
	v_add_u32_e32 v0, s48, v0
	v_add_u32_e32 v2, s46, v2
	v_cndmask_b32_e64 v2, v2, v0, s[90:91]
	v_mad_i32_i24 v221, v3, s33, v221
	v_ashrrev_i32_e32 v3, 31, v2
	v_lshl_add_u64 v[2:3], v[2:3], 0, s[96:97]
	v_mad_u64_u32 v[222:223], s[92:93], v2, s33, v[140:141]
	v_mad_i32_i24 v223, v3, s33, v223
	s_and_b32 s50, s49, 1
	s_mul_i32 s40, s50, 0x610
	s_add_i32 s51, s40, 0
	s_add_i32 s51, s51, 0x20500
	v_mov_b32_e32 v0, s51
	ds_read_b64 v[142:143], v0 offset:1536
	v_lshl_add_u32 v224, v159, 2, s51
	v_lshl_add_u32 v225, v160, 2, s51
	ds_read_b32 v224, v224
	ds_read_b32 v225, v225
	v_add_u32_e32 v0, v149, v161
	s_waitcnt vmcnt(9)
	ds_write_b128 v179, v[4:7]
	s_waitcnt vmcnt(8)
	ds_write_b128 v179, v[8:11] offset:34816
	s_waitcnt vmcnt(7)
	ds_write_b128 v180, v[12:15]
	s_waitcnt vmcnt(6)
	ds_write_b128 v180, v[16:19] offset:34816
	s_waitcnt vmcnt(5)
	ds_write_b128 v181, v[20:23]
	s_waitcnt vmcnt(4)
	ds_write_b128 v181, v[24:27] offset:34816
	s_waitcnt vmcnt(3)
	ds_write_b128 v182, v[28:31]
	s_waitcnt vmcnt(2)
	ds_write_b128 v182, v[32:35] offset:34816
	s_waitcnt vmcnt(1)
	ds_write_b128 v0, v[36:39]
	v_lshlrev_b32_e32 v2, 16, v36
	v_and_b32_e32 v3, 0xffff0000, v36
	s_waitcnt lgkmcnt(9)
	v_sub_f32_e32 v0, v224, v143
	v_mul_f32_e32 v0, 0x3fb8aa3b, v0
	v_exp_f32_e32 v0, v0
	s_nop 0
	v_pk_mul_f32 v[2:3], v[0:1], v[2:3] op_sel_hi:[0,1]
	v_cvt_pk_bf16_f32 v84, v2, v3
	v_lshlrev_b32_e32 v2, 16, v37
	v_and_b32_e32 v3, 0xffff0000, v37
	v_pk_mul_f32 v[2:3], v[0:1], v[2:3] op_sel_hi:[0,1]
	v_cvt_pk_bf16_f32 v85, v2, v3
	v_lshlrev_b32_e32 v2, 16, v38
	v_and_b32_e32 v3, 0xffff0000, v38
	v_pk_mul_f32 v[2:3], v[0:1], v[2:3] op_sel_hi:[0,1]
	v_cvt_pk_bf16_f32 v86, v2, v3
	v_lshlrev_b32_e32 v2, 16, v39
	v_and_b32_e32 v3, 0xffff0000, v39
	v_pk_mul_f32 v[2:3], v[0:1], v[2:3] op_sel_hi:[0,1]
	v_cvt_pk_bf16_f32 v87, v2, v3
	v_add_u32_e32 v2, v162, v148
	ds_write_b128 v2, v[84:87]
	s_and_saveexec_b64 s[40:41], s[10:11]
	s_cbranch_execz .LBB0_838
	v_cvt_pk_bf16_f32 v0, v0, 0
	v_mov_b32_e32 v2, v1
	v_mov_b32_e32 v3, v1
	ds_write_b128 v162, v[0:3] offset:128
	ds_write_b128 v162, v[208:211] offset:144
.LBB0_838:
	s_or_b64 exec, exec, s[40:41]
	v_add_u32_e32 v0, v149, v163
	s_waitcnt vmcnt(0)
	ds_write_b128 v0, v[40:43]
	v_lshlrev_b32_e32 v2, 16, v40
	v_and_b32_e32 v3, 0xffff0000, v40
	v_lshlrev_b32_e32 v84, 16, v41
	v_and_b32_e32 v85, 0xffff0000, v41
	v_sub_f32_e32 v0, v225, v143
	v_mul_f32_e32 v0, 0x3fb8aa3b, v0
	v_exp_f32_e32 v0, v0
	s_nop 0
	v_pk_mul_f32 v[2:3], v[0:1], v[2:3] op_sel_hi:[0,1]
	v_pk_mul_f32 v[86:87], v[0:1], v[84:85] op_sel_hi:[0,1]
	v_cvt_pk_bf16_f32 v84, v2, v3
	v_lshlrev_b32_e32 v2, 16, v42
	v_and_b32_e32 v3, 0xffff0000, v42
	v_pk_mul_f32 v[2:3], v[0:1], v[2:3] op_sel_hi:[0,1]
	v_cvt_pk_bf16_f32 v85, v86, v87
	v_cvt_pk_bf16_f32 v86, v2, v3
	v_lshlrev_b32_e32 v2, 16, v43
	v_and_b32_e32 v3, 0xffff0000, v43
	v_pk_mul_f32 v[2:3], v[0:1], v[2:3] op_sel_hi:[0,1]
	v_cvt_pk_bf16_f32 v87, v2, v3
	v_add_u32_e32 v2, v164, v148
	ds_write_b128 v2, v[84:87]
	s_and_saveexec_b64 s[40:41], s[10:11]
	s_cbranch_execz .LBB0_840
	v_cvt_pk_bf16_f32 v0, v0, 0
	v_mov_b32_e32 v2, v1
	v_mov_b32_e32 v3, v1
	ds_write_b128 v164, v[0:3] offset:128
	ds_write_b128 v164, v[208:211] offset:144
.LBB0_840:
	s_or_b64 exec, exec, s[40:41]
	s_add_i32 s49, s49, 1
	s_cmp_ge_u32 s49, s47
	s_cselect_b64 s[40:41], -1, 0
	s_cmp_lt_u32 s49, s47
	s_cbranch_scc0 .LBB0_843
	global_load_dwordx4 v[4:7], v[212:213], off
	s_nop 0
	global_load_dwordx4 v[8:11], v[212:213], off offset:1024
	s_nop 0
	global_load_dwordx4 v[12:15], v[214:215], off
	s_nop 0
	global_load_dwordx4 v[16:19], v[214:215], off offset:1024
	s_nop 0
	global_load_dwordx4 v[20:23], v[216:217], off
	s_nop 0
	global_load_dwordx4 v[24:27], v[216:217], off offset:1024
	s_nop 0
	global_load_dwordx4 v[28:31], v[218:219], off
	s_nop 0
	global_load_dwordx4 v[32:35], v[218:219], off offset:1024
	s_nop 0
	global_load_dwordx4 v[36:39], v[220:221], off offset:2048
	s_nop 0
	global_load_dwordx4 v[40:43], v[222:223], off offset:2048
	s_and_b64 vcc, exec, s[0:1]
	s_cbranch_vccz .LBB0_843
	v_sub_u32_e32 v3, 0, v144
	v_add_u32_e32 v0, s48, v144
	v_add_u32_e32 v84, s46, v3
	v_add_u32_e32 v2, 0x80, v0
	v_add_u32_e32 v3, 0xffffff7f, v84
	v_cndmask_b32_e64 v2, v3, v2, s[90:91]
	v_add_u32_e32 v84, 0xffffff7e, v84
	v_add_u32_e32 v0, 0x81, v0
	v_ashrrev_i32_e32 v3, 31, v2
	v_cndmask_b32_e64 v84, v84, v0, s[90:91]
	v_lshl_add_u64 v[2:3], v[2:3], 0, s[96:97]
	v_readlane_b32 s92, v255, 26
	v_ashrrev_i32_e32 v85, 31, v84
	v_lshlrev_b64 v[2:3], 6, v[2:3]
	v_readlane_b32 s93, v255, 27
	v_lshl_add_u64 v[84:85], v[84:85], 0, s[96:97]
	v_lshlrev_b64 v[84:85], 6, v[84:85]
	v_lshl_add_u64 v[2:3], s[92:93], 0, v[2:3]
	v_lshl_add_u64 v[84:85], s[92:93], 0, v[84:85]
	v_lshl_add_u64 v[86:87], v[2:3], 0, s[36:37]
	v_lshl_add_u64 v[2:3], v[2:3], 0, s[38:39]
	global_load_dword v132, v[86:87], off
	global_load_dword v123, v[2:3], off
	v_lshl_add_u64 v[2:3], v[84:85], 0, s[36:37]
	global_load_dword v133, v[2:3], off
	v_lshl_add_u64 v[2:3], v[84:85], 0, s[38:39]
	global_load_dword v207, v[2:3], off
